# attention unit loop rewritten by hand: 7-slot resident LDS ring for K then V^T rows, 8 barriers per unit instead of 20
# speedup vs baseline: 1.0060x; 1.0060x over previous
.LBB0_687:
	s_or_b64 exec, exec, s[4:5]
	s_add_u32 s74, s50, 0x10200000
	s_addc_u32 s75, s51, 0
	s_cmpk_gt_i32 s2, 0x1ff
	s_waitcnt lgkmcnt(0)
	s_barrier
	s_cbranch_scc1 .LBB0_867
	s_load_dwordx2 s[96:97], s[0:1], 0x58
	v_lshl_add_u32 v0, s91, 6, v234
	v_and_b32_e32 v1, 15, v234
	v_lshrrev_b32_e32 v2, 4, v234
	v_lshlrev_b32_e32 v226, 4, v0
	v_add_u32_e32 v227, 0x2000, v226
	v_lshrrev_b32_e32 v3, 4, v0
	v_mul_u32_u24_e32 v3, 0x110, v3
	v_and_b32_e32 v252, 15, v0
	v_lshl_add_u32 v228, v252, 4, v3
	v_lshrrev_b32_e32 v3, 3, v0
	v_and_b32_e32 v252, 7, v0
	v_lshlrev_b32_e32 v252, 4, v252
	v_lshl_add_u32 v229, v3, 14, v252
	v_add_u32_e32 v230, 0x100000, v229
	v_mul_u32_u24_e32 v3, 0x90, v3
	v_add_u32_e32 v231, v3, v252
	s_cmp_eq_u32 s92, 0
	s_cselect_b32 s29, 0, 8
	s_cmp_gt_u32 s92, 1
	s_cselect_b32 s29, 24, s29
	s_cmp_eq_u32 s92, 3
	s_cselect_b32 s29, 32, s29
	v_lshrrev_b32_e32 v3, 2, v1
	v_lshlrev_b32_e32 v3, 3, v3
	v_and_b32_e32 v252, 3, v1
	v_add3_u32 v3, v3, v252, s29
	v_mul_u32_u24_e32 v3, 0x110, v3
	v_lshl_add_u32 v232, v2, 4, v3
	v_mul_u32_u24_e32 v3, 0x90, v1
	v_lshl_add_u32 v252, v2, 3, s29
	v_lshl_add_u32 v233, v252, 1, v3
	v_lshlrev_b32_e32 v3, 8, v1
	v_lshl_add_u32 v235, v2, 4, v3
	v_lshlrev_b32_e32 v3, 12, v1
	v_lshl_add_u32 v236, v2, 3, v3
	v_lshlrev_b32_e32 v237, 4, v2
	v_xor_b32_e32 v238, 16, v234
	v_xor_b32_e32 v239, 32, v234
	v_lshlrev_b32_e32 v238, 2, v238
	v_lshlrev_b32_e32 v239, 2, v239
	v_lshl_add_u32 v3, s92, 4, v1
	v_subrev_u32_e32 v253, 8, v3
	v_max_i32_e32 v253, 0, v253
	v_min_i32_e32 v253, 48, v253
	v_add_u32_e32 v254, 16, v253
	v_add_u32_e32 v255, 0, v252
	v_cmp_ge_i32_e64 s[4:5], v255, v253
	v_cmp_lt_i32_e64 s[44:45], v255, v254
	v_sub_u32_e32 v255, v255, v3
	v_add_u32_e32 v255, 15, v255
	s_and_b64 s[4:5], s[4:5], s[44:45]
	v_max_i32_e32 v255, 0, v255
	v_min_i32_e32 v255, 30, v255
	v_lshlrev_b32_e32 v240, 2, v255
	v_add_u32_e32 v255, 1, v252
	v_cmp_ge_i32_e64 s[6:7], v255, v253
	v_cmp_lt_i32_e64 s[44:45], v255, v254
	v_sub_u32_e32 v255, v255, v3
	v_add_u32_e32 v255, 15, v255
	s_and_b64 s[6:7], s[6:7], s[44:45]
	v_max_i32_e32 v255, 0, v255
	v_min_i32_e32 v255, 30, v255
	v_lshlrev_b32_e32 v241, 2, v255
	v_add_u32_e32 v255, 2, v252
	v_cmp_ge_i32_e64 s[8:9], v255, v253
	v_cmp_lt_i32_e64 s[44:45], v255, v254
	v_sub_u32_e32 v255, v255, v3
	v_add_u32_e32 v255, 15, v255
	s_and_b64 s[8:9], s[8:9], s[44:45]
	v_max_i32_e32 v255, 0, v255
	v_min_i32_e32 v255, 30, v255
	v_lshlrev_b32_e32 v242, 2, v255
	v_add_u32_e32 v255, 3, v252
	v_cmp_ge_i32_e64 s[10:11], v255, v253
	v_cmp_lt_i32_e64 s[44:45], v255, v254
	v_sub_u32_e32 v255, v255, v3
	v_add_u32_e32 v255, 15, v255
	s_and_b64 s[10:11], s[10:11], s[44:45]
	v_max_i32_e32 v255, 0, v255
	v_min_i32_e32 v255, 30, v255
	v_lshlrev_b32_e32 v243, 2, v255
	v_add_u32_e32 v255, 4, v252
	v_cmp_ge_i32_e64 s[12:13], v255, v253
	v_cmp_lt_i32_e64 s[44:45], v255, v254
	v_sub_u32_e32 v255, v255, v3
	v_add_u32_e32 v255, 15, v255
	s_and_b64 s[12:13], s[12:13], s[44:45]
	v_max_i32_e32 v255, 0, v255
	v_min_i32_e32 v255, 30, v255
	v_lshlrev_b32_e32 v244, 2, v255
	v_add_u32_e32 v255, 5, v252
	v_cmp_ge_i32_e64 s[14:15], v255, v253
	v_cmp_lt_i32_e64 s[44:45], v255, v254
	v_sub_u32_e32 v255, v255, v3
	v_add_u32_e32 v255, 15, v255
	s_and_b64 s[14:15], s[14:15], s[44:45]
	v_max_i32_e32 v255, 0, v255
	v_min_i32_e32 v255, 30, v255
	v_lshlrev_b32_e32 v245, 2, v255
	v_add_u32_e32 v255, 6, v252
	v_cmp_ge_i32_e64 s[16:17], v255, v253
	v_cmp_lt_i32_e64 s[44:45], v255, v254
	v_sub_u32_e32 v255, v255, v3
	v_add_u32_e32 v255, 15, v255
	s_and_b64 s[16:17], s[16:17], s[44:45]
	v_max_i32_e32 v255, 0, v255
	v_min_i32_e32 v255, 30, v255
	v_lshlrev_b32_e32 v246, 2, v255
	v_add_u32_e32 v255, 7, v252
	v_cmp_ge_i32_e64 s[18:19], v255, v253
	v_cmp_lt_i32_e64 s[44:45], v255, v254
	v_sub_u32_e32 v255, v255, v3
	v_add_u32_e32 v255, 15, v255
	s_and_b64 s[18:19], s[18:19], s[44:45]
	v_max_i32_e32 v255, 0, v255
	v_min_i32_e32 v255, 30, v255
	v_lshlrev_b32_e32 v247, 2, v255
	s_mov_b32 s20, s2
	s_waitcnt lgkmcnt(0)
.Latt_unit:
	s_and_b32 s30, s20, 7
	s_lshr_b32 s31, s20, 8
	s_lshl_b32 s30, s30, 1
	s_add_i32 s30, s30, s31
	s_lshr_b32 s21, s30, 3
	s_and_b32 s22, s30, 7
	s_bfe_u32 s23, s20, 0x50003
	s_lshl_b32 s24, s23, 1
	s_add_i32 s24, s24, s88
	s_lshl_b32 s31, s23, 1
	s_add_i32 s25, s31, -4
	s_max_i32 s25, s25, 0
	s_min_i32 s25, s25, 56
	s_add_i32 s26, s24, -4
	s_max_i32 s26, s26, 0
	s_min_i32 s26, s26, 56
	s_sub_i32 s27, s26, s25
	s_add_i32 s28, s31, -3
	s_max_i32 s28, s28, 0
	s_min_i32 s28, s28, 56
	s_add_i32 s28, s28, 8
	s_sub_i32 s28, s28, s25
	s_lshl_b32 s30, s30, 12
	s_lshl_b32 s31, s25, 6
	s_add_i32 s31, s31, s30
	s_lshl_b32 s31, s31, 8
	s_add_u32 s34, s50, s31
	s_addc_u32 s35, s51, 0
	s_add_u32 s34, s34, 0xe200000
	s_addc_u32 s35, s35, 0
	s_lshl_b32 s31, s24, 6
	s_add_i32 s31, s31, s30
	s_lshl_b32 s77, s92, 4
	s_add_i32 s31, s77, s31
	s_lshl_b32 s31, s31, 8
	s_add_u32 s36, s50, s31
	s_addc_u32 s37, s51, 0
	s_add_u32 s36, s36, 0xd200000
	s_addc_u32 s37, s37, 0
	s_lshl_b32 s31, s22, 20
	s_lshl_b32 s77, s21, 12
	s_add_i32 s31, s77, s31
	s_lshl_b32 s77, s25, 6
	s_add_i32 s31, s77, s31
	s_lshl_b32 s31, s31, 1
	s_add_u32 s38, s50, s31
	s_addc_u32 s39, s51, 0
	s_add_u32 s38, s38, 0xf200000
	s_addc_u32 s39, s39, 0
	s_lshl_b32 s31, s21, 12
	s_lshl_b32 s77, s24, 6
	s_add_i32 s31, s77, s31
	s_lshl_b32 s77, s92, 4
	s_add_i32 s31, s77, s31
	s_lshl_b32 s31, s31, 11
	s_lshl_b32 s77, s22, 7
	s_add_i32 s31, s77, s31
	s_lshl_b32 s31, s31, 1
	s_add_u32 s40, s74, s31
	s_addc_u32 s41, s75, 0
	s_lshl_b32 s31, s22, 9
	s_add_u32 s60, s96, s31
	s_addc_u32 s61, s97, 0
	s_sub_i32 s31, s26, s24
	s_add_i32 s31, s31, 7
	s_mul_i32 s31, s31, 31
	s_mul_i32 s67, s22, 465
	s_add_i32 s67, s67, s31
	s_lshl_b32 s67, s67, 2
	global_load_dwordx4 v[76:79], v235, s[36:37] offset:0
	global_load_dwordx4 v[80:83], v235, s[36:37] offset:64
	global_load_dwordx4 v[84:87], v235, s[36:37] offset:128
	global_load_dwordx4 v[88:91], v235, s[36:37] offset:192
	global_load_dwordx4 v[4:7], v226, s[34:35]
	global_load_dwordx4 v[8:11], v227, s[34:35]
	s_add_u32 s34, s34, 0x4000
	s_addc_u32 s35, s35, 0
	global_load_dwordx4 v[12:15], v226, s[34:35]
	global_load_dwordx4 v[16:19], v227, s[34:35]
	s_add_u32 s34, s34, 0x4000
	s_addc_u32 s35, s35, 0
	global_load_dwordx4 v[20:23], v226, s[34:35]
	global_load_dwordx4 v[24:27], v227, s[34:35]
	s_add_u32 s34, s34, 0x4000
	s_addc_u32 s35, s35, 0
	global_load_dwordx4 v[28:31], v226, s[34:35]
	global_load_dwordx4 v[32:35], v227, s[34:35]
	s_add_u32 s34, s34, 0x4000
	s_addc_u32 s35, s35, 0
	global_load_dwordx4 v[36:39], v226, s[34:35]
	global_load_dwordx4 v[40:43], v227, s[34:35]
	s_add_u32 s34, s34, 0x4000
	s_addc_u32 s35, s35, 0
	global_load_dwordx4 v[44:47], v226, s[34:35]
	global_load_dwordx4 v[48:51], v227, s[34:35]
	s_add_u32 s34, s34, 0x4000
	s_addc_u32 s35, s35, 0
	global_load_dwordx4 v[52:55], v226, s[34:35]
	global_load_dwordx4 v[56:59], v227, s[34:35]
	s_add_u32 s34, s34, 0x4000
	s_addc_u32 s35, s35, 0
	global_load_dwordx4 v[60:63], v226, s[34:35]
	global_load_dwordx4 v[64:67], v227, s[34:35]
	s_add_u32 s34, s34, 0x4000
	s_addc_u32 s35, s35, 0
	s_cmp_lt_u32 s28, 9
	s_cbranch_scc1 .Latt_k8_skip
	global_load_dwordx4 v[68:71], v226, s[34:35]
	global_load_dwordx4 v[72:75], v227, s[34:35]
.Latt_k8_skip:
	s_waitcnt vmcnt(14)
	v_add_u32_e32 v0, 0x3c00, v228
	ds_write_b128 v0, v[4:7]
	ds_write_b128 v0, v[8:11] offset:8704
	s_waitcnt vmcnt(12)
	v_add_u32_e32 v0, 0x8400, v228
	ds_write_b128 v0, v[12:15]
	ds_write_b128 v0, v[16:19] offset:8704
	s_waitcnt vmcnt(10)
	v_add_u32_e32 v0, 0xcc00, v228
	ds_write_b128 v0, v[20:23]
	ds_write_b128 v0, v[24:27] offset:8704
	s_waitcnt vmcnt(8)
	v_add_u32_e32 v0, 0x11400, v228
	ds_write_b128 v0, v[28:31]
	ds_write_b128 v0, v[32:35] offset:8704
	s_waitcnt vmcnt(6)
	v_add_u32_e32 v0, 0x15c00, v228
	ds_write_b128 v0, v[36:39]
	ds_write_b128 v0, v[40:43] offset:8704
	s_waitcnt vmcnt(4)
	v_add_u32_e32 v0, 0x1a400, v228
	ds_write_b128 v0, v[44:47]
	ds_write_b128 v0, v[48:51] offset:8704
	s_waitcnt vmcnt(2)
	v_add_u32_e32 v0, 0x1ec00, v228
	ds_write_b128 v0, v[52:55]
	ds_write_b128 v0, v[56:59] offset:8704
	s_waitcnt lgkmcnt(0)
	s_barrier
	global_load_dwordx4 v[4:7], v229, s[38:39] offset:0
	global_load_dwordx4 v[8:11], v230, s[38:39] offset:0
	global_load_dwordx4 v[12:15], v229, s[38:39] offset:128
	global_load_dwordx4 v[16:19], v230, s[38:39] offset:128
	global_load_dwordx4 v[20:23], v229, s[38:39] offset:256
	global_load_dwordx4 v[24:27], v230, s[38:39] offset:256
	global_load_dwordx4 v[28:31], v229, s[38:39] offset:384
	global_load_dwordx4 v[32:35], v230, s[38:39] offset:384
	global_load_dwordx4 v[36:39], v229, s[38:39] offset:512
	global_load_dwordx4 v[40:43], v230, s[38:39] offset:512
	global_load_dwordx4 v[44:47], v229, s[38:39] offset:640
	global_load_dwordx4 v[48:51], v230, s[38:39] offset:640
	global_load_dwordx4 v[52:55], v229, s[38:39] offset:768
	global_load_dwordx4 v[56:59], v230, s[38:39] offset:768
	s_add_i32 s30, s27, 0
	s_add_i32 s31, s30, -7
	s_cmp_lt_i32 s30, 7
	s_cselect_b32 s30, s30, s31
	s_mul_i32 s30, s30, 0x4800
	s_add_i32 s30, s30, 0x3c00
	v_add_u32_e32 v0, s30, v232
	ds_read_b128 v[156:159], v0 offset:0
	ds_read_b128 v[160:163], v0 offset:64
	ds_read_b128 v[164:167], v0 offset:128
	ds_read_b128 v[168:171], v0 offset:192
	ds_read_b128 v[172:175], v0 offset:1088
	ds_read_b128 v[176:179], v0 offset:1152
	ds_read_b128 v[180:183], v0 offset:1216
	ds_read_b128 v[184:187], v0 offset:1280
	s_waitcnt lgkmcnt(0)
	v_mfma_f32_16x16x32_bf16 v[92:95], v[156:159], v[76:79], 0
	v_mfma_f32_16x16x32_bf16 v[96:99], v[172:175], v[76:79], 0
	v_mfma_f32_16x16x32_bf16 v[92:95], v[160:163], v[80:83], v[92:95]
	v_mfma_f32_16x16x32_bf16 v[96:99], v[176:179], v[80:83], v[96:99]
	v_mfma_f32_16x16x32_bf16 v[92:95], v[164:167], v[84:87], v[92:95]
	v_mfma_f32_16x16x32_bf16 v[96:99], v[180:183], v[84:87], v[96:99]
	v_mfma_f32_16x16x32_bf16 v[92:95], v[168:171], v[88:91], v[92:95]
	v_mfma_f32_16x16x32_bf16 v[96:99], v[184:187], v[88:91], v[96:99]
	s_add_i32 s30, s27, 1
	s_add_i32 s31, s30, -7
	s_cmp_lt_i32 s30, 7
	s_cselect_b32 s30, s30, s31
	s_mul_i32 s30, s30, 0x4800
	s_add_i32 s30, s30, 0x3c00
	v_add_u32_e32 v0, s30, v232
	ds_read_b128 v[156:159], v0 offset:0
	ds_read_b128 v[160:163], v0 offset:64
	ds_read_b128 v[164:167], v0 offset:128
	ds_read_b128 v[168:171], v0 offset:192
	ds_read_b128 v[172:175], v0 offset:1088
	ds_read_b128 v[176:179], v0 offset:1152
	ds_read_b128 v[180:183], v0 offset:1216
	ds_read_b128 v[184:187], v0 offset:1280
	s_waitcnt lgkmcnt(0)
	v_mfma_f32_16x16x32_bf16 v[100:103], v[156:159], v[76:79], 0
	v_mfma_f32_16x16x32_bf16 v[104:107], v[172:175], v[76:79], 0
	v_mfma_f32_16x16x32_bf16 v[100:103], v[160:163], v[80:83], v[100:103]
	v_mfma_f32_16x16x32_bf16 v[104:107], v[176:179], v[80:83], v[104:107]
	v_mfma_f32_16x16x32_bf16 v[100:103], v[164:167], v[84:87], v[100:103]
	v_mfma_f32_16x16x32_bf16 v[104:107], v[180:183], v[84:87], v[104:107]
	v_mfma_f32_16x16x32_bf16 v[100:103], v[168:171], v[88:91], v[100:103]
	v_mfma_f32_16x16x32_bf16 v[104:107], v[184:187], v[88:91], v[104:107]
	s_add_i32 s30, s27, 2
	s_add_i32 s31, s30, -7
	s_cmp_lt_i32 s30, 7
	s_cselect_b32 s30, s30, s31
	s_mul_i32 s30, s30, 0x4800
	s_add_i32 s30, s30, 0x3c00
	v_add_u32_e32 v0, s30, v232
	ds_read_b128 v[156:159], v0 offset:0
	ds_read_b128 v[160:163], v0 offset:64
	ds_read_b128 v[164:167], v0 offset:128
	ds_read_b128 v[168:171], v0 offset:192
	ds_read_b128 v[172:175], v0 offset:1088
	ds_read_b128 v[176:179], v0 offset:1152
	ds_read_b128 v[180:183], v0 offset:1216
	ds_read_b128 v[184:187], v0 offset:1280
	s_waitcnt lgkmcnt(0)
	v_mfma_f32_16x16x32_bf16 v[108:111], v[156:159], v[76:79], 0
	v_mfma_f32_16x16x32_bf16 v[112:115], v[172:175], v[76:79], 0
	v_mfma_f32_16x16x32_bf16 v[108:111], v[160:163], v[80:83], v[108:111]
	v_mfma_f32_16x16x32_bf16 v[112:115], v[176:179], v[80:83], v[112:115]
	v_mfma_f32_16x16x32_bf16 v[108:111], v[164:167], v[84:87], v[108:111]
	v_mfma_f32_16x16x32_bf16 v[112:115], v[180:183], v[84:87], v[112:115]
	v_mfma_f32_16x16x32_bf16 v[108:111], v[168:171], v[88:91], v[108:111]
	v_mfma_f32_16x16x32_bf16 v[112:115], v[184:187], v[88:91], v[112:115]
	s_add_i32 s30, s27, 3
	s_add_i32 s31, s30, -7
	s_cmp_lt_i32 s30, 7
	s_cselect_b32 s30, s30, s31
	s_mul_i32 s30, s30, 0x4800
	s_add_i32 s30, s30, 0x3c00
	v_add_u32_e32 v0, s30, v232
	ds_read_b128 v[156:159], v0 offset:0
	ds_read_b128 v[160:163], v0 offset:64
	ds_read_b128 v[164:167], v0 offset:128
	ds_read_b128 v[168:171], v0 offset:192
	ds_read_b128 v[172:175], v0 offset:1088
	ds_read_b128 v[176:179], v0 offset:1152
	ds_read_b128 v[180:183], v0 offset:1216
	ds_read_b128 v[184:187], v0 offset:1280
	s_waitcnt lgkmcnt(0)
	v_mfma_f32_16x16x32_bf16 v[116:119], v[156:159], v[76:79], 0
	v_mfma_f32_16x16x32_bf16 v[120:123], v[172:175], v[76:79], 0
	v_mfma_f32_16x16x32_bf16 v[116:119], v[160:163], v[80:83], v[116:119]
	v_mfma_f32_16x16x32_bf16 v[120:123], v[176:179], v[80:83], v[120:123]
	v_mfma_f32_16x16x32_bf16 v[116:119], v[164:167], v[84:87], v[116:119]
	v_mfma_f32_16x16x32_bf16 v[120:123], v[180:183], v[84:87], v[120:123]
	v_mfma_f32_16x16x32_bf16 v[116:119], v[168:171], v[88:91], v[116:119]
	v_mfma_f32_16x16x32_bf16 v[120:123], v[184:187], v[88:91], v[120:123]
	s_add_i32 s30, s27, 4
	s_add_i32 s31, s30, -7
	s_cmp_lt_i32 s30, 7
	s_cselect_b32 s30, s30, s31
	s_mul_i32 s30, s30, 0x4800
	s_add_i32 s30, s30, 0x3c00
	v_add_u32_e32 v0, s30, v232
	ds_read_b128 v[156:159], v0 offset:0
	ds_read_b128 v[160:163], v0 offset:64
	ds_read_b128 v[164:167], v0 offset:128
	ds_read_b128 v[168:171], v0 offset:192
	ds_read_b128 v[172:175], v0 offset:1088
	ds_read_b128 v[176:179], v0 offset:1152
	ds_read_b128 v[180:183], v0 offset:1216
	ds_read_b128 v[184:187], v0 offset:1280
	s_waitcnt lgkmcnt(0)
	v_mfma_f32_16x16x32_bf16 v[124:127], v[156:159], v[76:79], 0
	v_mfma_f32_16x16x32_bf16 v[128:131], v[172:175], v[76:79], 0
	v_mfma_f32_16x16x32_bf16 v[124:127], v[160:163], v[80:83], v[124:127]
	v_mfma_f32_16x16x32_bf16 v[128:131], v[176:179], v[80:83], v[128:131]
	v_mfma_f32_16x16x32_bf16 v[124:127], v[164:167], v[84:87], v[124:127]
	v_mfma_f32_16x16x32_bf16 v[128:131], v[180:183], v[84:87], v[128:131]
	v_mfma_f32_16x16x32_bf16 v[124:127], v[168:171], v[88:91], v[124:127]
	v_mfma_f32_16x16x32_bf16 v[128:131], v[184:187], v[88:91], v[128:131]
	s_add_i32 s30, s27, 5
	s_add_i32 s31, s30, -7
	s_cmp_lt_i32 s30, 7
	s_cselect_b32 s30, s30, s31
	s_mul_i32 s30, s30, 0x4800
	s_add_i32 s30, s30, 0x3c00
	v_add_u32_e32 v0, s30, v232
	ds_read_b128 v[156:159], v0 offset:0
	ds_read_b128 v[160:163], v0 offset:64
	ds_read_b128 v[164:167], v0 offset:128
	ds_read_b128 v[168:171], v0 offset:192
	ds_read_b128 v[172:175], v0 offset:1088
	ds_read_b128 v[176:179], v0 offset:1152
	ds_read_b128 v[180:183], v0 offset:1216
	ds_read_b128 v[184:187], v0 offset:1280
	s_waitcnt lgkmcnt(0)
	v_mfma_f32_16x16x32_bf16 v[132:135], v[156:159], v[76:79], 0
	v_mfma_f32_16x16x32_bf16 v[136:139], v[172:175], v[76:79], 0
	v_mfma_f32_16x16x32_bf16 v[132:135], v[160:163], v[80:83], v[132:135]
	v_mfma_f32_16x16x32_bf16 v[136:139], v[176:179], v[80:83], v[136:139]
	v_mfma_f32_16x16x32_bf16 v[132:135], v[164:167], v[84:87], v[132:135]
	v_mfma_f32_16x16x32_bf16 v[136:139], v[180:183], v[84:87], v[136:139]
	v_mfma_f32_16x16x32_bf16 v[132:135], v[168:171], v[88:91], v[132:135]
	v_mfma_f32_16x16x32_bf16 v[136:139], v[184:187], v[88:91], v[136:139]
	s_cmp_lg_u32 s27, 0
	s_cbranch_scc1 .Latt_s6a_skip
	s_add_i32 s30, s27, 6
	s_add_i32 s31, s30, -7
	s_cmp_lt_i32 s30, 7
	s_cselect_b32 s30, s30, s31
	s_mul_i32 s30, s30, 0x4800
	s_add_i32 s30, s30, 0x3c00
	v_add_u32_e32 v0, s30, v232
	ds_read_b128 v[156:159], v0 offset:0
	ds_read_b128 v[160:163], v0 offset:64
	ds_read_b128 v[164:167], v0 offset:128
	ds_read_b128 v[168:171], v0 offset:192
	ds_read_b128 v[172:175], v0 offset:1088
	ds_read_b128 v[176:179], v0 offset:1152
	ds_read_b128 v[180:183], v0 offset:1216
	ds_read_b128 v[184:187], v0 offset:1280
	s_waitcnt lgkmcnt(0)
	v_mfma_f32_16x16x32_bf16 v[140:143], v[156:159], v[76:79], 0
	v_mfma_f32_16x16x32_bf16 v[144:147], v[172:175], v[76:79], 0
	v_mfma_f32_16x16x32_bf16 v[140:143], v[160:163], v[80:83], v[140:143]
	v_mfma_f32_16x16x32_bf16 v[144:147], v[176:179], v[80:83], v[144:147]
	v_mfma_f32_16x16x32_bf16 v[140:143], v[164:167], v[84:87], v[140:143]
	v_mfma_f32_16x16x32_bf16 v[144:147], v[180:183], v[84:87], v[144:147]
	v_mfma_f32_16x16x32_bf16 v[140:143], v[168:171], v[88:91], v[140:143]
	v_mfma_f32_16x16x32_bf16 v[144:147], v[184:187], v[88:91], v[144:147]
.Latt_s6a_skip:
	s_barrier
	s_waitcnt vmcnt(14)
	v_add_u32_e32 v0, 0x3c00, v228
	ds_write_b128 v0, v[60:63]
	ds_write_b128 v0, v[64:67] offset:8704
	s_cmp_lt_u32 s28, 9
	s_cbranch_scc1 .Latt_kw8_skip
	v_add_u32_e32 v0, 0x8400, v228
	ds_write_b128 v0, v[68:71]
	ds_write_b128 v0, v[72:75] offset:8704
.Latt_kw8_skip:
	s_waitcnt lgkmcnt(0)
	s_barrier
	global_load_dwordx4 v[60:63], v229, s[38:39] offset:896
	global_load_dwordx4 v[64:67], v230, s[38:39] offset:896
	s_cmp_lt_u32 s28, 9
	s_cbranch_scc1 .Latt_v8_skip
	global_load_dwordx4 v[68:71], v229, s[38:39] offset:1024
	global_load_dwordx4 v[72:75], v230, s[38:39] offset:1024
.Latt_v8_skip:
	s_cmp_eq_u32 s27, 0
	s_cbranch_scc1 .Latt_s6b_skip
	s_add_i32 s30, s27, 6
	s_add_i32 s31, s30, -7
	s_cmp_lt_i32 s30, 7
	s_cselect_b32 s30, s30, s31
	s_mul_i32 s30, s30, 0x4800
	s_add_i32 s30, s30, 0x3c00
	v_add_u32_e32 v0, s30, v232
	ds_read_b128 v[156:159], v0 offset:0
	ds_read_b128 v[160:163], v0 offset:64
	ds_read_b128 v[164:167], v0 offset:128
	ds_read_b128 v[168:171], v0 offset:192
	ds_read_b128 v[172:175], v0 offset:1088
	ds_read_b128 v[176:179], v0 offset:1152
	ds_read_b128 v[180:183], v0 offset:1216
	ds_read_b128 v[184:187], v0 offset:1280
	s_waitcnt lgkmcnt(0)
	v_mfma_f32_16x16x32_bf16 v[140:143], v[156:159], v[76:79], 0
	v_mfma_f32_16x16x32_bf16 v[144:147], v[172:175], v[76:79], 0
	v_mfma_f32_16x16x32_bf16 v[140:143], v[160:163], v[80:83], v[140:143]
	v_mfma_f32_16x16x32_bf16 v[144:147], v[176:179], v[80:83], v[144:147]
	v_mfma_f32_16x16x32_bf16 v[140:143], v[164:167], v[84:87], v[140:143]
	v_mfma_f32_16x16x32_bf16 v[144:147], v[180:183], v[84:87], v[144:147]
	v_mfma_f32_16x16x32_bf16 v[140:143], v[168:171], v[88:91], v[140:143]
	v_mfma_f32_16x16x32_bf16 v[144:147], v[184:187], v[88:91], v[144:147]
.Latt_s6b_skip:
	s_add_i32 s30, s27, 7
	s_add_i32 s31, s30, -7
	s_cmp_lt_i32 s30, 7
	s_cselect_b32 s30, s30, s31
	s_mul_i32 s30, s30, 0x4800
	s_add_i32 s30, s30, 0x3c00
	v_add_u32_e32 v0, s30, v232
	ds_read_b128 v[156:159], v0 offset:0
	ds_read_b128 v[160:163], v0 offset:64
	ds_read_b128 v[164:167], v0 offset:128
	ds_read_b128 v[168:171], v0 offset:192
	ds_read_b128 v[172:175], v0 offset:1088
	ds_read_b128 v[176:179], v0 offset:1152
	ds_read_b128 v[180:183], v0 offset:1216
	ds_read_b128 v[184:187], v0 offset:1280
	s_waitcnt lgkmcnt(0)
	v_mfma_f32_16x16x32_bf16 v[148:151], v[156:159], v[76:79], 0
	v_mfma_f32_16x16x32_bf16 v[152:155], v[172:175], v[76:79], 0
	v_mfma_f32_16x16x32_bf16 v[148:151], v[160:163], v[80:83], v[148:151]
	v_mfma_f32_16x16x32_bf16 v[152:155], v[176:179], v[80:83], v[152:155]
	v_mfma_f32_16x16x32_bf16 v[148:151], v[164:167], v[84:87], v[148:151]
	v_mfma_f32_16x16x32_bf16 v[152:155], v[180:183], v[84:87], v[152:155]
	v_mfma_f32_16x16x32_bf16 v[148:151], v[168:171], v[88:91], v[148:151]
	v_mfma_f32_16x16x32_bf16 v[152:155], v[184:187], v[88:91], v[152:155]
	s_barrier
	s_cmp_lt_u32 s28, 9
	s_cbranch_scc1 .Latt_vw_n8
	s_waitcnt vmcnt(4)
	s_branch .Latt_vw_go

.Latt_vw_go:
	v_add_u32_e32 v0, 0x3c00, v231
	ds_write_b128 v0, v[4:7]
	ds_write_b128 v0, v[8:11] offset:9216
	v_add_u32_e32 v0, 0x8400, v231
	ds_write_b128 v0, v[12:15]
	ds_write_b128 v0, v[16:19] offset:9216
	v_add_u32_e32 v0, 0xcc00, v231
	ds_write_b128 v0, v[20:23]
	ds_write_b128 v0, v[24:27] offset:9216
	v_add_u32_e32 v0, 0x11400, v231
	ds_write_b128 v0, v[28:31]
	ds_write_b128 v0, v[32:35] offset:9216
	v_add_u32_e32 v0, 0x15c00, v231
	ds_write_b128 v0, v[36:39]
	ds_write_b128 v0, v[40:43] offset:9216
	v_add_u32_e32 v0, 0x1a400, v231
	ds_write_b128 v0, v[44:47]
	ds_write_b128 v0, v[48:51] offset:9216
	v_add_u32_e32 v0, 0x1ec00, v231
	ds_write_b128 v0, v[52:55]
	ds_write_b128 v0, v[56:59] offset:9216
	v_mov_b32_e32 v251, 0xf149f2ca
	v_add_u32_e32 v156, s67, v240
	v_add_u32_e32 v157, s67, v241
	v_add_u32_e32 v158, s67, v242
	v_add_u32_e32 v159, s67, v243
	v_add_u32_e32 v160, s67, v244
	v_add_u32_e32 v161, s67, v245
	v_add_u32_e32 v162, s67, v246
	v_add_u32_e32 v163, s67, v247
	v_mov_b32_e32 v248, 0xff61b1e6
	ds_read_b32 v164, v156 offset:0
	ds_read_b32 v165, v157 offset:0
	ds_read_b32 v166, v158 offset:0
	ds_read_b32 v167, v159 offset:0
	ds_read_b32 v168, v160 offset:0
	ds_read_b32 v169, v161 offset:0
	ds_read_b32 v170, v162 offset:0
	ds_read_b32 v171, v163 offset:0
	s_waitcnt lgkmcnt(0)
	ds_read_b32 v172, v156 offset:124
	ds_read_b32 v173, v157 offset:124
	ds_read_b32 v174, v158 offset:124
	ds_read_b32 v175, v159 offset:124
	ds_read_b32 v176, v160 offset:124
	ds_read_b32 v177, v161 offset:124
	ds_read_b32 v178, v162 offset:124
	ds_read_b32 v179, v163 offset:124
	v_fmamk_f32 v92, v92, 0x3db504f3, v164
	v_fmamk_f32 v93, v93, 0x3db504f3, v165
	v_fmamk_f32 v94, v94, 0x3db504f3, v166
	v_fmamk_f32 v95, v95, 0x3db504f3, v167
	v_fmamk_f32 v96, v96, 0x3db504f3, v168
	v_fmamk_f32 v97, v97, 0x3db504f3, v169
	v_fmamk_f32 v98, v98, 0x3db504f3, v170
	v_fmamk_f32 v99, v99, 0x3db504f3, v171
	v_cndmask_b32_e64 v92, v251, v92, s[4:5]
	v_cndmask_b32_e64 v93, v251, v93, s[6:7]
	v_cndmask_b32_e64 v94, v251, v94, s[8:9]
	v_cndmask_b32_e64 v95, v251, v95, s[10:11]
	v_cndmask_b32_e64 v96, v251, v96, s[12:13]
	v_cndmask_b32_e64 v97, v251, v97, s[14:15]
	v_cndmask_b32_e64 v98, v251, v98, s[16:17]
	v_cndmask_b32_e64 v99, v251, v99, s[18:19]
	v_max3_f32 v248, v248, v92, v93
	v_max3_f32 v248, v248, v94, v95
	v_max3_f32 v248, v248, v96, v97
	v_max3_f32 v248, v248, v98, v99
	s_waitcnt lgkmcnt(0)
	ds_read_b32 v164, v156 offset:248
	ds_read_b32 v165, v157 offset:248
	ds_read_b32 v166, v158 offset:248
	ds_read_b32 v167, v159 offset:248
	ds_read_b32 v168, v160 offset:248
	ds_read_b32 v169, v161 offset:248
	ds_read_b32 v170, v162 offset:248
	ds_read_b32 v171, v163 offset:248
	v_fmamk_f32 v100, v100, 0x3db504f3, v172
	v_fmamk_f32 v101, v101, 0x3db504f3, v173
	v_fmamk_f32 v102, v102, 0x3db504f3, v174
	v_fmamk_f32 v103, v103, 0x3db504f3, v175
	v_fmamk_f32 v104, v104, 0x3db504f3, v176
	v_fmamk_f32 v105, v105, 0x3db504f3, v177
	v_fmamk_f32 v106, v106, 0x3db504f3, v178
	v_fmamk_f32 v107, v107, 0x3db504f3, v179
	v_cndmask_b32_e64 v100, v251, v100, s[4:5]
	v_cndmask_b32_e64 v101, v251, v101, s[6:7]
	v_cndmask_b32_e64 v102, v251, v102, s[8:9]
	v_cndmask_b32_e64 v103, v251, v103, s[10:11]
	v_cndmask_b32_e64 v104, v251, v104, s[12:13]
	v_cndmask_b32_e64 v105, v251, v105, s[14:15]
	v_cndmask_b32_e64 v106, v251, v106, s[16:17]
	v_cndmask_b32_e64 v107, v251, v107, s[18:19]
	v_max3_f32 v248, v248, v100, v101
	v_max3_f32 v248, v248, v102, v103
	v_max3_f32 v248, v248, v104, v105
	v_max3_f32 v248, v248, v106, v107
	s_waitcnt lgkmcnt(0)
	ds_read_b32 v172, v156 offset:372
	ds_read_b32 v173, v157 offset:372
	ds_read_b32 v174, v158 offset:372
	ds_read_b32 v175, v159 offset:372
	ds_read_b32 v176, v160 offset:372
	ds_read_b32 v177, v161 offset:372
	ds_read_b32 v178, v162 offset:372
	ds_read_b32 v179, v163 offset:372
	v_fmamk_f32 v108, v108, 0x3db504f3, v164
	v_fmamk_f32 v109, v109, 0x3db504f3, v165
	v_fmamk_f32 v110, v110, 0x3db504f3, v166
	v_fmamk_f32 v111, v111, 0x3db504f3, v167
	v_fmamk_f32 v112, v112, 0x3db504f3, v168
	v_fmamk_f32 v113, v113, 0x3db504f3, v169
	v_fmamk_f32 v114, v114, 0x3db504f3, v170
	v_fmamk_f32 v115, v115, 0x3db504f3, v171
	v_cndmask_b32_e64 v108, v251, v108, s[4:5]
	v_cndmask_b32_e64 v109, v251, v109, s[6:7]
	v_cndmask_b32_e64 v110, v251, v110, s[8:9]
	v_cndmask_b32_e64 v111, v251, v111, s[10:11]
	v_cndmask_b32_e64 v112, v251, v112, s[12:13]
	v_cndmask_b32_e64 v113, v251, v113, s[14:15]
	v_cndmask_b32_e64 v114, v251, v114, s[16:17]
	v_cndmask_b32_e64 v115, v251, v115, s[18:19]
	v_max3_f32 v248, v248, v108, v109
	v_max3_f32 v248, v248, v110, v111
	v_max3_f32 v248, v248, v112, v113
	v_max3_f32 v248, v248, v114, v115
	s_waitcnt lgkmcnt(0)
	ds_read_b32 v164, v156 offset:496
	ds_read_b32 v165, v157 offset:496
	ds_read_b32 v166, v158 offset:496
	ds_read_b32 v167, v159 offset:496
	ds_read_b32 v168, v160 offset:496
	ds_read_b32 v169, v161 offset:496
	ds_read_b32 v170, v162 offset:496
	ds_read_b32 v171, v163 offset:496
	v_fmamk_f32 v116, v116, 0x3db504f3, v172
	v_fmamk_f32 v117, v117, 0x3db504f3, v173
	v_fmamk_f32 v118, v118, 0x3db504f3, v174
	v_fmamk_f32 v119, v119, 0x3db504f3, v175
	v_fmamk_f32 v120, v120, 0x3db504f3, v176
	v_fmamk_f32 v121, v121, 0x3db504f3, v177
	v_fmamk_f32 v122, v122, 0x3db504f3, v178
	v_fmamk_f32 v123, v123, 0x3db504f3, v179
	v_cndmask_b32_e64 v116, v251, v116, s[4:5]
	v_cndmask_b32_e64 v117, v251, v117, s[6:7]
	v_cndmask_b32_e64 v118, v251, v118, s[8:9]
	v_cndmask_b32_e64 v119, v251, v119, s[10:11]
	v_cndmask_b32_e64 v120, v251, v120, s[12:13]
	v_cndmask_b32_e64 v121, v251, v121, s[14:15]
	v_cndmask_b32_e64 v122, v251, v122, s[16:17]
	v_cndmask_b32_e64 v123, v251, v123, s[18:19]
	v_max3_f32 v248, v248, v116, v117
	v_max3_f32 v248, v248, v118, v119
	v_max3_f32 v248, v248, v120, v121
	v_max3_f32 v248, v248, v122, v123
	s_waitcnt lgkmcnt(0)
	ds_read_b32 v172, v156 offset:620
	ds_read_b32 v173, v157 offset:620
	ds_read_b32 v174, v158 offset:620
	ds_read_b32 v175, v159 offset:620
	ds_read_b32 v176, v160 offset:620
	ds_read_b32 v177, v161 offset:620
	ds_read_b32 v178, v162 offset:620
	ds_read_b32 v179, v163 offset:620
	v_fmamk_f32 v124, v124, 0x3db504f3, v164
	v_fmamk_f32 v125, v125, 0x3db504f3, v165
	v_fmamk_f32 v126, v126, 0x3db504f3, v166
	v_fmamk_f32 v127, v127, 0x3db504f3, v167
	v_fmamk_f32 v128, v128, 0x3db504f3, v168
	v_fmamk_f32 v129, v129, 0x3db504f3, v169
	v_fmamk_f32 v130, v130, 0x3db504f3, v170
	v_fmamk_f32 v131, v131, 0x3db504f3, v171
	v_cndmask_b32_e64 v124, v251, v124, s[4:5]
	v_cndmask_b32_e64 v125, v251, v125, s[6:7]
	v_cndmask_b32_e64 v126, v251, v126, s[8:9]
	v_cndmask_b32_e64 v127, v251, v127, s[10:11]
	v_cndmask_b32_e64 v128, v251, v128, s[12:13]
	v_cndmask_b32_e64 v129, v251, v129, s[14:15]
	v_cndmask_b32_e64 v130, v251, v130, s[16:17]
	v_cndmask_b32_e64 v131, v251, v131, s[18:19]
	v_max3_f32 v248, v248, v124, v125
	v_max3_f32 v248, v248, v126, v127
	v_max3_f32 v248, v248, v128, v129
	v_max3_f32 v248, v248, v130, v131
	s_waitcnt lgkmcnt(0)
	ds_read_b32 v164, v156 offset:744
	ds_read_b32 v165, v157 offset:744
	ds_read_b32 v166, v158 offset:744
	ds_read_b32 v167, v159 offset:744
	ds_read_b32 v168, v160 offset:744
	ds_read_b32 v169, v161 offset:744
	ds_read_b32 v170, v162 offset:744
	ds_read_b32 v171, v163 offset:744
	v_fmamk_f32 v132, v132, 0x3db504f3, v172
	v_fmamk_f32 v133, v133, 0x3db504f3, v173
	v_fmamk_f32 v134, v134, 0x3db504f3, v174
	v_fmamk_f32 v135, v135, 0x3db504f3, v175
	v_fmamk_f32 v136, v136, 0x3db504f3, v176
	v_fmamk_f32 v137, v137, 0x3db504f3, v177
	v_fmamk_f32 v138, v138, 0x3db504f3, v178
	v_fmamk_f32 v139, v139, 0x3db504f3, v179
	v_cndmask_b32_e64 v132, v251, v132, s[4:5]
	v_cndmask_b32_e64 v133, v251, v133, s[6:7]
	v_cndmask_b32_e64 v134, v251, v134, s[8:9]
	v_cndmask_b32_e64 v135, v251, v135, s[10:11]
	v_cndmask_b32_e64 v136, v251, v136, s[12:13]
	v_cndmask_b32_e64 v137, v251, v137, s[14:15]
	v_cndmask_b32_e64 v138, v251, v138, s[16:17]
	v_cndmask_b32_e64 v139, v251, v139, s[18:19]
	v_max3_f32 v248, v248, v132, v133
	v_max3_f32 v248, v248, v134, v135
	v_max3_f32 v248, v248, v136, v137
	v_max3_f32 v248, v248, v138, v139
	s_waitcnt lgkmcnt(0)
	ds_read_b32 v172, v156 offset:868
	ds_read_b32 v173, v157 offset:868
	ds_read_b32 v174, v158 offset:868
	ds_read_b32 v175, v159 offset:868
	ds_read_b32 v176, v160 offset:868
	ds_read_b32 v177, v161 offset:868
	ds_read_b32 v178, v162 offset:868
	ds_read_b32 v179, v163 offset:868
	v_fmamk_f32 v140, v140, 0x3db504f3, v164
	v_fmamk_f32 v141, v141, 0x3db504f3, v165
	v_fmamk_f32 v142, v142, 0x3db504f3, v166
	v_fmamk_f32 v143, v143, 0x3db504f3, v167
	v_fmamk_f32 v144, v144, 0x3db504f3, v168
	v_fmamk_f32 v145, v145, 0x3db504f3, v169
	v_fmamk_f32 v146, v146, 0x3db504f3, v170
	v_fmamk_f32 v147, v147, 0x3db504f3, v171
	v_cndmask_b32_e64 v140, v251, v140, s[4:5]
	v_cndmask_b32_e64 v141, v251, v141, s[6:7]
	v_cndmask_b32_e64 v142, v251, v142, s[8:9]
	v_cndmask_b32_e64 v143, v251, v143, s[10:11]
	v_cndmask_b32_e64 v144, v251, v144, s[12:13]
	v_cndmask_b32_e64 v145, v251, v145, s[14:15]
	v_cndmask_b32_e64 v146, v251, v146, s[16:17]
	v_cndmask_b32_e64 v147, v251, v147, s[18:19]
	v_max3_f32 v248, v248, v140, v141
	v_max3_f32 v248, v248, v142, v143
	v_max3_f32 v248, v248, v144, v145
	v_max3_f32 v248, v248, v146, v147
	s_waitcnt lgkmcnt(0)
	v_fmamk_f32 v148, v148, 0x3db504f3, v172
	v_fmamk_f32 v149, v149, 0x3db504f3, v173
	v_fmamk_f32 v150, v150, 0x3db504f3, v174
	v_fmamk_f32 v151, v151, 0x3db504f3, v175
	v_fmamk_f32 v152, v152, 0x3db504f3, v176
	v_fmamk_f32 v153, v153, 0x3db504f3, v177
	v_fmamk_f32 v154, v154, 0x3db504f3, v178
	v_fmamk_f32 v155, v155, 0x3db504f3, v179
	v_cndmask_b32_e64 v148, v251, v148, s[4:5]
	v_cndmask_b32_e64 v149, v251, v149, s[6:7]
	v_cndmask_b32_e64 v150, v251, v150, s[8:9]
	v_cndmask_b32_e64 v151, v251, v151, s[10:11]
	v_cndmask_b32_e64 v152, v251, v152, s[12:13]
	v_cndmask_b32_e64 v153, v251, v153, s[14:15]
	v_cndmask_b32_e64 v154, v251, v154, s[16:17]
	v_cndmask_b32_e64 v155, v251, v155, s[18:19]
	v_max3_f32 v248, v248, v148, v149
	v_max3_f32 v248, v248, v150, v151
	v_max3_f32 v248, v248, v152, v153
	v_max3_f32 v248, v248, v154, v155
	ds_bpermute_b32 v252, v238, v248
	s_waitcnt lgkmcnt(0)
	v_max_f32_e32 v248, v248, v252
	ds_bpermute_b32 v252, v239, v248
	s_waitcnt lgkmcnt(0)
	v_max_f32_e32 v248, v248, v252
	v_mov_b32_e32 v249, 0
	v_sub_f32_e32 v92, v92, v248
	v_sub_f32_e32 v93, v93, v248
	v_sub_f32_e32 v94, v94, v248
	v_sub_f32_e32 v95, v95, v248
	v_sub_f32_e32 v96, v96, v248
	v_sub_f32_e32 v97, v97, v248
	v_sub_f32_e32 v98, v98, v248
	v_sub_f32_e32 v99, v99, v248
	v_mul_f32_e32 v92, 0x3fb8aa3b, v92
	v_mul_f32_e32 v93, 0x3fb8aa3b, v93
	v_mul_f32_e32 v94, 0x3fb8aa3b, v94
	v_mul_f32_e32 v95, 0x3fb8aa3b, v95
	v_mul_f32_e32 v96, 0x3fb8aa3b, v96
	v_mul_f32_e32 v97, 0x3fb8aa3b, v97
	v_mul_f32_e32 v98, 0x3fb8aa3b, v98
	v_mul_f32_e32 v99, 0x3fb8aa3b, v99
	v_exp_f32_e32 v92, v92
	v_exp_f32_e32 v93, v93
	v_exp_f32_e32 v94, v94
	v_exp_f32_e32 v95, v95
	v_exp_f32_e32 v96, v96
	v_exp_f32_e32 v97, v97
	v_exp_f32_e32 v98, v98
	v_exp_f32_e32 v99, v99
	s_nop 0
	v_add_f32_e32 v249, v249, v92
	v_add_f32_e32 v249, v249, v93
	v_add_f32_e32 v249, v249, v94
	v_add_f32_e32 v249, v249, v95
	v_add_f32_e32 v249, v249, v96
	v_add_f32_e32 v249, v249, v97
	v_add_f32_e32 v249, v249, v98
	v_add_f32_e32 v249, v249, v99
	v_sub_f32_e32 v100, v100, v248
	v_sub_f32_e32 v101, v101, v248
	v_sub_f32_e32 v102, v102, v248
	v_sub_f32_e32 v103, v103, v248
	v_sub_f32_e32 v104, v104, v248
	v_sub_f32_e32 v105, v105, v248
	v_sub_f32_e32 v106, v106, v248
	v_sub_f32_e32 v107, v107, v248
	v_mul_f32_e32 v100, 0x3fb8aa3b, v100
	v_mul_f32_e32 v101, 0x3fb8aa3b, v101
	v_mul_f32_e32 v102, 0x3fb8aa3b, v102
	v_mul_f32_e32 v103, 0x3fb8aa3b, v103
	v_mul_f32_e32 v104, 0x3fb8aa3b, v104
	v_mul_f32_e32 v105, 0x3fb8aa3b, v105
	v_mul_f32_e32 v106, 0x3fb8aa3b, v106
	v_mul_f32_e32 v107, 0x3fb8aa3b, v107
	v_exp_f32_e32 v100, v100
	v_exp_f32_e32 v101, v101
	v_exp_f32_e32 v102, v102
	v_exp_f32_e32 v103, v103
	v_exp_f32_e32 v104, v104
	v_exp_f32_e32 v105, v105
	v_exp_f32_e32 v106, v106
	v_exp_f32_e32 v107, v107
	s_nop 0
	v_add_f32_e32 v249, v249, v100
	v_add_f32_e32 v249, v249, v101
	v_add_f32_e32 v249, v249, v102
	v_add_f32_e32 v249, v249, v103
	v_add_f32_e32 v249, v249, v104
	v_add_f32_e32 v249, v249, v105
	v_add_f32_e32 v249, v249, v106
	v_add_f32_e32 v249, v249, v107
	v_sub_f32_e32 v108, v108, v248
	v_sub_f32_e32 v109, v109, v248
	v_sub_f32_e32 v110, v110, v248
	v_sub_f32_e32 v111, v111, v248
	v_sub_f32_e32 v112, v112, v248
	v_sub_f32_e32 v113, v113, v248
	v_sub_f32_e32 v114, v114, v248
	v_sub_f32_e32 v115, v115, v248
	v_mul_f32_e32 v108, 0x3fb8aa3b, v108
	v_mul_f32_e32 v109, 0x3fb8aa3b, v109
	v_mul_f32_e32 v110, 0x3fb8aa3b, v110
	v_mul_f32_e32 v111, 0x3fb8aa3b, v111
	v_mul_f32_e32 v112, 0x3fb8aa3b, v112
	v_mul_f32_e32 v113, 0x3fb8aa3b, v113
	v_mul_f32_e32 v114, 0x3fb8aa3b, v114
	v_mul_f32_e32 v115, 0x3fb8aa3b, v115
	v_exp_f32_e32 v108, v108
	v_exp_f32_e32 v109, v109
	v_exp_f32_e32 v110, v110
	v_exp_f32_e32 v111, v111
	v_exp_f32_e32 v112, v112
	v_exp_f32_e32 v113, v113
	v_exp_f32_e32 v114, v114
	v_exp_f32_e32 v115, v115
	s_nop 0
	v_add_f32_e32 v249, v249, v108
	v_add_f32_e32 v249, v249, v109
	v_add_f32_e32 v249, v249, v110
	v_add_f32_e32 v249, v249, v111
	v_add_f32_e32 v249, v249, v112
	v_add_f32_e32 v249, v249, v113
	v_add_f32_e32 v249, v249, v114
	v_add_f32_e32 v249, v249, v115
	v_sub_f32_e32 v116, v116, v248
	v_sub_f32_e32 v117, v117, v248
	v_sub_f32_e32 v118, v118, v248
	v_sub_f32_e32 v119, v119, v248
	v_sub_f32_e32 v120, v120, v248
	v_sub_f32_e32 v121, v121, v248
	v_sub_f32_e32 v122, v122, v248
	v_sub_f32_e32 v123, v123, v248
	v_mul_f32_e32 v116, 0x3fb8aa3b, v116
	v_mul_f32_e32 v117, 0x3fb8aa3b, v117
	v_mul_f32_e32 v118, 0x3fb8aa3b, v118
	v_mul_f32_e32 v119, 0x3fb8aa3b, v119
	v_mul_f32_e32 v120, 0x3fb8aa3b, v120
	v_mul_f32_e32 v121, 0x3fb8aa3b, v121
	v_mul_f32_e32 v122, 0x3fb8aa3b, v122
	v_mul_f32_e32 v123, 0x3fb8aa3b, v123
	v_exp_f32_e32 v116, v116
	v_exp_f32_e32 v117, v117
	v_exp_f32_e32 v118, v118
	v_exp_f32_e32 v119, v119
	v_exp_f32_e32 v120, v120
	v_exp_f32_e32 v121, v121
	v_exp_f32_e32 v122, v122
	v_exp_f32_e32 v123, v123
	s_nop 0
	v_add_f32_e32 v249, v249, v116
	v_add_f32_e32 v249, v249, v117
	v_add_f32_e32 v249, v249, v118
	v_add_f32_e32 v249, v249, v119
	v_add_f32_e32 v249, v249, v120
	v_add_f32_e32 v249, v249, v121
	v_add_f32_e32 v249, v249, v122
	v_add_f32_e32 v249, v249, v123
	v_sub_f32_e32 v124, v124, v248
	v_sub_f32_e32 v125, v125, v248
	v_sub_f32_e32 v126, v126, v248
	v_sub_f32_e32 v127, v127, v248
	v_sub_f32_e32 v128, v128, v248
	v_sub_f32_e32 v129, v129, v248
	v_sub_f32_e32 v130, v130, v248
	v_sub_f32_e32 v131, v131, v248
	v_mul_f32_e32 v124, 0x3fb8aa3b, v124
	v_mul_f32_e32 v125, 0x3fb8aa3b, v125
	v_mul_f32_e32 v126, 0x3fb8aa3b, v126
	v_mul_f32_e32 v127, 0x3fb8aa3b, v127
	v_mul_f32_e32 v128, 0x3fb8aa3b, v128
	v_mul_f32_e32 v129, 0x3fb8aa3b, v129
	v_mul_f32_e32 v130, 0x3fb8aa3b, v130
	v_mul_f32_e32 v131, 0x3fb8aa3b, v131
	v_exp_f32_e32 v124, v124
	v_exp_f32_e32 v125, v125
	v_exp_f32_e32 v126, v126
	v_exp_f32_e32 v127, v127
	v_exp_f32_e32 v128, v128
	v_exp_f32_e32 v129, v129
	v_exp_f32_e32 v130, v130
	v_exp_f32_e32 v131, v131
	s_nop 0
	v_add_f32_e32 v249, v249, v124
	v_add_f32_e32 v249, v249, v125
	v_add_f32_e32 v249, v249, v126
	v_add_f32_e32 v249, v249, v127
	v_add_f32_e32 v249, v249, v128
	v_add_f32_e32 v249, v249, v129
	v_add_f32_e32 v249, v249, v130
	v_add_f32_e32 v249, v249, v131
	v_sub_f32_e32 v132, v132, v248
	v_sub_f32_e32 v133, v133, v248
	v_sub_f32_e32 v134, v134, v248
	v_sub_f32_e32 v135, v135, v248
	v_sub_f32_e32 v136, v136, v248
	v_sub_f32_e32 v137, v137, v248
	v_sub_f32_e32 v138, v138, v248
	v_sub_f32_e32 v139, v139, v248
	v_mul_f32_e32 v132, 0x3fb8aa3b, v132
	v_mul_f32_e32 v133, 0x3fb8aa3b, v133
	v_mul_f32_e32 v134, 0x3fb8aa3b, v134
	v_mul_f32_e32 v135, 0x3fb8aa3b, v135
	v_mul_f32_e32 v136, 0x3fb8aa3b, v136
	v_mul_f32_e32 v137, 0x3fb8aa3b, v137
	v_mul_f32_e32 v138, 0x3fb8aa3b, v138
	v_mul_f32_e32 v139, 0x3fb8aa3b, v139
	v_exp_f32_e32 v132, v132
	v_exp_f32_e32 v133, v133
	v_exp_f32_e32 v134, v134
	v_exp_f32_e32 v135, v135
	v_exp_f32_e32 v136, v136
	v_exp_f32_e32 v137, v137
	v_exp_f32_e32 v138, v138
	v_exp_f32_e32 v139, v139
	s_nop 0
	v_add_f32_e32 v249, v249, v132
	v_add_f32_e32 v249, v249, v133
	v_add_f32_e32 v249, v249, v134
	v_add_f32_e32 v249, v249, v135
	v_add_f32_e32 v249, v249, v136
	v_add_f32_e32 v249, v249, v137
	v_add_f32_e32 v249, v249, v138
	v_add_f32_e32 v249, v249, v139
	v_sub_f32_e32 v140, v140, v248
	v_sub_f32_e32 v141, v141, v248
	v_sub_f32_e32 v142, v142, v248
	v_sub_f32_e32 v143, v143, v248
	v_sub_f32_e32 v144, v144, v248
	v_sub_f32_e32 v145, v145, v248
	v_sub_f32_e32 v146, v146, v248
	v_sub_f32_e32 v147, v147, v248
	v_mul_f32_e32 v140, 0x3fb8aa3b, v140
	v_mul_f32_e32 v141, 0x3fb8aa3b, v141
	v_mul_f32_e32 v142, 0x3fb8aa3b, v142
	v_mul_f32_e32 v143, 0x3fb8aa3b, v143
	v_mul_f32_e32 v144, 0x3fb8aa3b, v144
	v_mul_f32_e32 v145, 0x3fb8aa3b, v145
	v_mul_f32_e32 v146, 0x3fb8aa3b, v146
	v_mul_f32_e32 v147, 0x3fb8aa3b, v147
	v_exp_f32_e32 v140, v140
	v_exp_f32_e32 v141, v141
	v_exp_f32_e32 v142, v142
	v_exp_f32_e32 v143, v143
	v_exp_f32_e32 v144, v144
	v_exp_f32_e32 v145, v145
	v_exp_f32_e32 v146, v146
	v_exp_f32_e32 v147, v147
	s_nop 0
	v_add_f32_e32 v249, v249, v140
	v_add_f32_e32 v249, v249, v141
	v_add_f32_e32 v249, v249, v142
	v_add_f32_e32 v249, v249, v143
	v_add_f32_e32 v249, v249, v144
	v_add_f32_e32 v249, v249, v145
	v_add_f32_e32 v249, v249, v146
	v_add_f32_e32 v249, v249, v147
	v_sub_f32_e32 v148, v148, v248
	v_sub_f32_e32 v149, v149, v248
	v_sub_f32_e32 v150, v150, v248
	v_sub_f32_e32 v151, v151, v248
	v_sub_f32_e32 v152, v152, v248
	v_sub_f32_e32 v153, v153, v248
	v_sub_f32_e32 v154, v154, v248
	v_sub_f32_e32 v155, v155, v248
	v_mul_f32_e32 v148, 0x3fb8aa3b, v148
	v_mul_f32_e32 v149, 0x3fb8aa3b, v149
	v_mul_f32_e32 v150, 0x3fb8aa3b, v150
	v_mul_f32_e32 v151, 0x3fb8aa3b, v151
	v_mul_f32_e32 v152, 0x3fb8aa3b, v152
	v_mul_f32_e32 v153, 0x3fb8aa3b, v153
	v_mul_f32_e32 v154, 0x3fb8aa3b, v154
	v_mul_f32_e32 v155, 0x3fb8aa3b, v155
	v_exp_f32_e32 v148, v148
	v_exp_f32_e32 v149, v149
	v_exp_f32_e32 v150, v150
	v_exp_f32_e32 v151, v151
	v_exp_f32_e32 v152, v152
	v_exp_f32_e32 v153, v153
	v_exp_f32_e32 v154, v154
	v_exp_f32_e32 v155, v155
	s_nop 0
	v_add_f32_e32 v249, v249, v148
	v_add_f32_e32 v249, v249, v149
	v_add_f32_e32 v249, v249, v150
	v_add_f32_e32 v249, v249, v151
	v_add_f32_e32 v249, v249, v152
	v_add_f32_e32 v249, v249, v153
	v_add_f32_e32 v249, v249, v154
	v_add_f32_e32 v249, v249, v155
	ds_bpermute_b32 v252, v238, v249
	s_waitcnt lgkmcnt(0)
	v_add_f32_e32 v249, v249, v252
	ds_bpermute_b32 v252, v239, v249
	s_waitcnt lgkmcnt(0)
	v_add_f32_e32 v249, v249, v252
	s_barrier
	v_cvt_pk_bf16_f32 v220, v92, v93
	v_cvt_pk_bf16_f32 v221, v94, v95
	v_cvt_pk_bf16_f32 v222, v96, v97
	v_cvt_pk_bf16_f32 v223, v98, v99
	s_add_i32 s30, s27, 0
	s_add_i32 s31, s30, -7
	s_cmp_lt_i32 s30, 7
	s_cselect_b32 s30, s30, s31
	s_mul_i32 s30, s30, 0x4800
	s_add_i32 s30, s30, 0x3c00
	v_add_u32_e32 v0, s30, v233
	ds_read_b128 v[156:159], v0 offset:0
	ds_read_b128 v[160:163], v0 offset:2304
	ds_read_b128 v[164:167], v0 offset:4608
	ds_read_b128 v[168:171], v0 offset:6912
	ds_read_b128 v[172:175], v0 offset:9216
	ds_read_b128 v[176:179], v0 offset:11520
	ds_read_b128 v[180:183], v0 offset:13824
	ds_read_b128 v[184:187], v0 offset:16128
	s_waitcnt lgkmcnt(0)
	v_mfma_f32_16x16x32_bf16 v[188:191], v[156:159], v[220:223], 0
	v_mfma_f32_16x16x32_bf16 v[192:195], v[160:163], v[220:223], 0
	v_mfma_f32_16x16x32_bf16 v[196:199], v[164:167], v[220:223], 0
	v_mfma_f32_16x16x32_bf16 v[200:203], v[168:171], v[220:223], 0
	v_mfma_f32_16x16x32_bf16 v[204:207], v[172:175], v[220:223], 0
	v_mfma_f32_16x16x32_bf16 v[208:211], v[176:179], v[220:223], 0
	v_mfma_f32_16x16x32_bf16 v[212:215], v[180:183], v[220:223], 0
	v_mfma_f32_16x16x32_bf16 v[216:219], v[184:187], v[220:223], 0
	v_cvt_pk_bf16_f32 v220, v100, v101
	v_cvt_pk_bf16_f32 v221, v102, v103
	v_cvt_pk_bf16_f32 v222, v104, v105
	v_cvt_pk_bf16_f32 v223, v106, v107
	s_add_i32 s30, s27, 1
	s_add_i32 s31, s30, -7
	s_cmp_lt_i32 s30, 7
	s_cselect_b32 s30, s30, s31
	s_mul_i32 s30, s30, 0x4800
	s_add_i32 s30, s30, 0x3c00
	v_add_u32_e32 v0, s30, v233
	ds_read_b128 v[156:159], v0 offset:0
	ds_read_b128 v[160:163], v0 offset:2304
	ds_read_b128 v[164:167], v0 offset:4608
	ds_read_b128 v[168:171], v0 offset:6912
	ds_read_b128 v[172:175], v0 offset:9216
	ds_read_b128 v[176:179], v0 offset:11520
	ds_read_b128 v[180:183], v0 offset:13824
	ds_read_b128 v[184:187], v0 offset:16128
	s_waitcnt lgkmcnt(0)
	v_mfma_f32_16x16x32_bf16 v[188:191], v[156:159], v[220:223], v[188:191]
	v_mfma_f32_16x16x32_bf16 v[192:195], v[160:163], v[220:223], v[192:195]
	v_mfma_f32_16x16x32_bf16 v[196:199], v[164:167], v[220:223], v[196:199]
	v_mfma_f32_16x16x32_bf16 v[200:203], v[168:171], v[220:223], v[200:203]
	v_mfma_f32_16x16x32_bf16 v[204:207], v[172:175], v[220:223], v[204:207]
	v_mfma_f32_16x16x32_bf16 v[208:211], v[176:179], v[220:223], v[208:211]
	v_mfma_f32_16x16x32_bf16 v[212:215], v[180:183], v[220:223], v[212:215]
	v_mfma_f32_16x16x32_bf16 v[216:219], v[184:187], v[220:223], v[216:219]
	v_cvt_pk_bf16_f32 v220, v108, v109
	v_cvt_pk_bf16_f32 v221, v110, v111
	v_cvt_pk_bf16_f32 v222, v112, v113
	v_cvt_pk_bf16_f32 v223, v114, v115
	s_add_i32 s30, s27, 2
	s_add_i32 s31, s30, -7
	s_cmp_lt_i32 s30, 7
	s_cselect_b32 s30, s30, s31
	s_mul_i32 s30, s30, 0x4800
	s_add_i32 s30, s30, 0x3c00
	v_add_u32_e32 v0, s30, v233
	ds_read_b128 v[156:159], v0 offset:0
	ds_read_b128 v[160:163], v0 offset:2304
	ds_read_b128 v[164:167], v0 offset:4608
	ds_read_b128 v[168:171], v0 offset:6912
	ds_read_b128 v[172:175], v0 offset:9216
	ds_read_b128 v[176:179], v0 offset:11520
	ds_read_b128 v[180:183], v0 offset:13824
	ds_read_b128 v[184:187], v0 offset:16128
	s_waitcnt lgkmcnt(0)
	v_mfma_f32_16x16x32_bf16 v[188:191], v[156:159], v[220:223], v[188:191]
	v_mfma_f32_16x16x32_bf16 v[192:195], v[160:163], v[220:223], v[192:195]
	v_mfma_f32_16x16x32_bf16 v[196:199], v[164:167], v[220:223], v[196:199]
	v_mfma_f32_16x16x32_bf16 v[200:203], v[168:171], v[220:223], v[200:203]
	v_mfma_f32_16x16x32_bf16 v[204:207], v[172:175], v[220:223], v[204:207]
	v_mfma_f32_16x16x32_bf16 v[208:211], v[176:179], v[220:223], v[208:211]
	v_mfma_f32_16x16x32_bf16 v[212:215], v[180:183], v[220:223], v[212:215]
	v_mfma_f32_16x16x32_bf16 v[216:219], v[184:187], v[220:223], v[216:219]
	v_cvt_pk_bf16_f32 v220, v116, v117
	v_cvt_pk_bf16_f32 v221, v118, v119
	v_cvt_pk_bf16_f32 v222, v120, v121
	v_cvt_pk_bf16_f32 v223, v122, v123
	s_add_i32 s30, s27, 3
	s_add_i32 s31, s30, -7
	s_cmp_lt_i32 s30, 7
	s_cselect_b32 s30, s30, s31
	s_mul_i32 s30, s30, 0x4800
	s_add_i32 s30, s30, 0x3c00
	v_add_u32_e32 v0, s30, v233
	ds_read_b128 v[156:159], v0 offset:0
	ds_read_b128 v[160:163], v0 offset:2304
	ds_read_b128 v[164:167], v0 offset:4608
	ds_read_b128 v[168:171], v0 offset:6912
	ds_read_b128 v[172:175], v0 offset:9216
	ds_read_b128 v[176:179], v0 offset:11520
	ds_read_b128 v[180:183], v0 offset:13824
	ds_read_b128 v[184:187], v0 offset:16128
	s_waitcnt lgkmcnt(0)
	v_mfma_f32_16x16x32_bf16 v[188:191], v[156:159], v[220:223], v[188:191]
	v_mfma_f32_16x16x32_bf16 v[192:195], v[160:163], v[220:223], v[192:195]
	v_mfma_f32_16x16x32_bf16 v[196:199], v[164:167], v[220:223], v[196:199]
	v_mfma_f32_16x16x32_bf16 v[200:203], v[168:171], v[220:223], v[200:203]
	v_mfma_f32_16x16x32_bf16 v[204:207], v[172:175], v[220:223], v[204:207]
	v_mfma_f32_16x16x32_bf16 v[208:211], v[176:179], v[220:223], v[208:211]
	v_mfma_f32_16x16x32_bf16 v[212:215], v[180:183], v[220:223], v[212:215]
	v_mfma_f32_16x16x32_bf16 v[216:219], v[184:187], v[220:223], v[216:219]
	v_cvt_pk_bf16_f32 v220, v124, v125
	v_cvt_pk_bf16_f32 v221, v126, v127
	v_cvt_pk_bf16_f32 v222, v128, v129
	v_cvt_pk_bf16_f32 v223, v130, v131
	s_add_i32 s30, s27, 4
	s_add_i32 s31, s30, -7
	s_cmp_lt_i32 s30, 7
	s_cselect_b32 s30, s30, s31
	s_mul_i32 s30, s30, 0x4800
	s_add_i32 s30, s30, 0x3c00
	v_add_u32_e32 v0, s30, v233
	ds_read_b128 v[156:159], v0 offset:0
	ds_read_b128 v[160:163], v0 offset:2304
	ds_read_b128 v[164:167], v0 offset:4608
	ds_read_b128 v[168:171], v0 offset:6912
	ds_read_b128 v[172:175], v0 offset:9216
	ds_read_b128 v[176:179], v0 offset:11520
	ds_read_b128 v[180:183], v0 offset:13824
	ds_read_b128 v[184:187], v0 offset:16128
	s_waitcnt lgkmcnt(0)
	v_mfma_f32_16x16x32_bf16 v[188:191], v[156:159], v[220:223], v[188:191]
	v_mfma_f32_16x16x32_bf16 v[192:195], v[160:163], v[220:223], v[192:195]
	v_mfma_f32_16x16x32_bf16 v[196:199], v[164:167], v[220:223], v[196:199]
	v_mfma_f32_16x16x32_bf16 v[200:203], v[168:171], v[220:223], v[200:203]
	v_mfma_f32_16x16x32_bf16 v[204:207], v[172:175], v[220:223], v[204:207]
	v_mfma_f32_16x16x32_bf16 v[208:211], v[176:179], v[220:223], v[208:211]
	v_mfma_f32_16x16x32_bf16 v[212:215], v[180:183], v[220:223], v[212:215]
	v_mfma_f32_16x16x32_bf16 v[216:219], v[184:187], v[220:223], v[216:219]
	v_cvt_pk_bf16_f32 v220, v132, v133
	v_cvt_pk_bf16_f32 v221, v134, v135
	v_cvt_pk_bf16_f32 v222, v136, v137
	v_cvt_pk_bf16_f32 v223, v138, v139
	s_add_i32 s30, s27, 5
	s_add_i32 s31, s30, -7
	s_cmp_lt_i32 s30, 7
	s_cselect_b32 s30, s30, s31
	s_mul_i32 s30, s30, 0x4800
	s_add_i32 s30, s30, 0x3c00
	v_add_u32_e32 v0, s30, v233
	ds_read_b128 v[156:159], v0 offset:0
	ds_read_b128 v[160:163], v0 offset:2304
	ds_read_b128 v[164:167], v0 offset:4608
	ds_read_b128 v[168:171], v0 offset:6912
	ds_read_b128 v[172:175], v0 offset:9216
	ds_read_b128 v[176:179], v0 offset:11520
	ds_read_b128 v[180:183], v0 offset:13824
	ds_read_b128 v[184:187], v0 offset:16128
	s_waitcnt lgkmcnt(0)
	v_mfma_f32_16x16x32_bf16 v[188:191], v[156:159], v[220:223], v[188:191]
	v_mfma_f32_16x16x32_bf16 v[192:195], v[160:163], v[220:223], v[192:195]
	v_mfma_f32_16x16x32_bf16 v[196:199], v[164:167], v[220:223], v[196:199]
	v_mfma_f32_16x16x32_bf16 v[200:203], v[168:171], v[220:223], v[200:203]
	v_mfma_f32_16x16x32_bf16 v[204:207], v[172:175], v[220:223], v[204:207]
	v_mfma_f32_16x16x32_bf16 v[208:211], v[176:179], v[220:223], v[208:211]
	v_mfma_f32_16x16x32_bf16 v[212:215], v[180:183], v[220:223], v[212:215]
	v_mfma_f32_16x16x32_bf16 v[216:219], v[184:187], v[220:223], v[216:219]
	s_cmp_lg_u32 s27, 0
	s_cbranch_scc1 .Latt_p6a_skip
	v_cvt_pk_bf16_f32 v220, v140, v141
	v_cvt_pk_bf16_f32 v221, v142, v143
	v_cvt_pk_bf16_f32 v222, v144, v145
	v_cvt_pk_bf16_f32 v223, v146, v147
	s_add_i32 s30, s27, 6
	s_add_i32 s31, s30, -7
	s_cmp_lt_i32 s30, 7
	s_cselect_b32 s30, s30, s31
	s_mul_i32 s30, s30, 0x4800
	s_add_i32 s30, s30, 0x3c00
	v_add_u32_e32 v0, s30, v233
	ds_read_b128 v[156:159], v0 offset:0
	ds_read_b128 v[160:163], v0 offset:2304
	ds_read_b128 v[164:167], v0 offset:4608
	ds_read_b128 v[168:171], v0 offset:6912
	ds_read_b128 v[172:175], v0 offset:9216
	ds_read_b128 v[176:179], v0 offset:11520
	ds_read_b128 v[180:183], v0 offset:13824
	ds_read_b128 v[184:187], v0 offset:16128
	s_waitcnt lgkmcnt(0)
	v_mfma_f32_16x16x32_bf16 v[188:191], v[156:159], v[220:223], v[188:191]
	v_mfma_f32_16x16x32_bf16 v[192:195], v[160:163], v[220:223], v[192:195]
	v_mfma_f32_16x16x32_bf16 v[196:199], v[164:167], v[220:223], v[196:199]
	v_mfma_f32_16x16x32_bf16 v[200:203], v[168:171], v[220:223], v[200:203]
	v_mfma_f32_16x16x32_bf16 v[204:207], v[172:175], v[220:223], v[204:207]
	v_mfma_f32_16x16x32_bf16 v[208:211], v[176:179], v[220:223], v[208:211]
	v_mfma_f32_16x16x32_bf16 v[212:215], v[180:183], v[220:223], v[212:215]
	v_mfma_f32_16x16x32_bf16 v[216:219], v[184:187], v[220:223], v[216:219]
.Latt_p6a_skip:
	s_barrier
	s_waitcnt vmcnt(0)
	v_add_u32_e32 v0, 0x3c00, v231
	ds_write_b128 v0, v[60:63]
	ds_write_b128 v0, v[64:67] offset:9216
	s_cmp_lt_u32 s28, 9
	s_cbranch_scc1 .Latt_vw8_skip
	v_add_u32_e32 v0, 0x8400, v231
	ds_write_b128 v0, v[68:71]
	ds_write_b128 v0, v[72:75] offset:9216
.Latt_vw8_skip:
	s_waitcnt lgkmcnt(0)
	s_barrier
	global_load_dwordx4 v[4:7], v237, s[60:61] offset:0
	global_load_dwordx4 v[8:11], v237, s[60:61] offset:64
	global_load_dwordx4 v[12:15], v237, s[60:61] offset:128
	global_load_dwordx4 v[16:19], v237, s[60:61] offset:192
	global_load_dwordx4 v[20:23], v237, s[60:61] offset:256
	global_load_dwordx4 v[24:27], v237, s[60:61] offset:320
	global_load_dwordx4 v[28:31], v237, s[60:61] offset:384
	global_load_dwordx4 v[32:35], v237, s[60:61] offset:448
	s_cmp_eq_u32 s27, 0
	s_cbranch_scc1 .Latt_p6b_skip
	v_cvt_pk_bf16_f32 v220, v140, v141
	v_cvt_pk_bf16_f32 v221, v142, v143
	v_cvt_pk_bf16_f32 v222, v144, v145
	v_cvt_pk_bf16_f32 v223, v146, v147
	s_add_i32 s30, s27, 6
	s_add_i32 s31, s30, -7
	s_cmp_lt_i32 s30, 7
	s_cselect_b32 s30, s30, s31
	s_mul_i32 s30, s30, 0x4800
	s_add_i32 s30, s30, 0x3c00
	v_add_u32_e32 v0, s30, v233
	ds_read_b128 v[156:159], v0 offset:0
	ds_read_b128 v[160:163], v0 offset:2304
	ds_read_b128 v[164:167], v0 offset:4608
	ds_read_b128 v[168:171], v0 offset:6912
	ds_read_b128 v[172:175], v0 offset:9216
	ds_read_b128 v[176:179], v0 offset:11520
	ds_read_b128 v[180:183], v0 offset:13824
	ds_read_b128 v[184:187], v0 offset:16128
	s_waitcnt lgkmcnt(0)
	v_mfma_f32_16x16x32_bf16 v[188:191], v[156:159], v[220:223], v[188:191]
	v_mfma_f32_16x16x32_bf16 v[192:195], v[160:163], v[220:223], v[192:195]
	v_mfma_f32_16x16x32_bf16 v[196:199], v[164:167], v[220:223], v[196:199]
	v_mfma_f32_16x16x32_bf16 v[200:203], v[168:171], v[220:223], v[200:203]
	v_mfma_f32_16x16x32_bf16 v[204:207], v[172:175], v[220:223], v[204:207]
	v_mfma_f32_16x16x32_bf16 v[208:211], v[176:179], v[220:223], v[208:211]
	v_mfma_f32_16x16x32_bf16 v[212:215], v[180:183], v[220:223], v[212:215]
	v_mfma_f32_16x16x32_bf16 v[216:219], v[184:187], v[220:223], v[216:219]
.Latt_p6b_skip:
	v_cvt_pk_bf16_f32 v220, v148, v149
	v_cvt_pk_bf16_f32 v221, v150, v151
	v_cvt_pk_bf16_f32 v222, v152, v153
	v_cvt_pk_bf16_f32 v223, v154, v155
	s_add_i32 s30, s27, 7
	s_add_i32 s31, s30, -7
	s_cmp_lt_i32 s30, 7
	s_cselect_b32 s30, s30, s31
	s_mul_i32 s30, s30, 0x4800
	s_add_i32 s30, s30, 0x3c00
	v_add_u32_e32 v0, s30, v233
	ds_read_b128 v[156:159], v0 offset:0
	ds_read_b128 v[160:163], v0 offset:2304
	ds_read_b128 v[164:167], v0 offset:4608
	ds_read_b128 v[168:171], v0 offset:6912
	ds_read_b128 v[172:175], v0 offset:9216
	ds_read_b128 v[176:179], v0 offset:11520
	ds_read_b128 v[180:183], v0 offset:13824
	ds_read_b128 v[184:187], v0 offset:16128
	s_waitcnt lgkmcnt(0)
	v_mfma_f32_16x16x32_bf16 v[188:191], v[156:159], v[220:223], v[188:191]
	v_mfma_f32_16x16x32_bf16 v[192:195], v[160:163], v[220:223], v[192:195]
	v_mfma_f32_16x16x32_bf16 v[196:199], v[164:167], v[220:223], v[196:199]
	v_mfma_f32_16x16x32_bf16 v[200:203], v[168:171], v[220:223], v[200:203]
	v_mfma_f32_16x16x32_bf16 v[204:207], v[172:175], v[220:223], v[204:207]
	v_mfma_f32_16x16x32_bf16 v[208:211], v[176:179], v[220:223], v[208:211]
	v_mfma_f32_16x16x32_bf16 v[212:215], v[180:183], v[220:223], v[212:215]
	v_mfma_f32_16x16x32_bf16 v[216:219], v[184:187], v[220:223], v[216:219]
	v_div_scale_f32 v252, s[44:45], v249, v249, 1.0
	v_rcp_f32_e32 v253, v252
	v_div_scale_f32 v254, vcc, 1.0, v249, 1.0
	s_nop 0
	v_fma_f32 v255, -v252, v253, 1.0
	v_fmac_f32_e32 v253, v255, v253
	v_mul_f32_e32 v255, v254, v253
	v_fma_f32 v248, -v252, v255, v254
	v_fmac_f32_e32 v255, v248, v253
	v_fma_f32 v252, -v252, v255, v254
	v_div_fmas_f32 v252, v252, v253, v255
	v_div_fixup_f32 v252, v252, v249, 1.0
	s_nop 7
	v_pk_mul_f32 v[188:189], v[188:189], v[252:253] op_sel_hi:[1,0]
	v_pk_mul_f32 v[190:191], v[190:191], v[252:253] op_sel_hi:[1,0]
	v_pk_mul_f32 v[192:193], v[192:193], v[252:253] op_sel_hi:[1,0]
	v_pk_mul_f32 v[194:195], v[194:195], v[252:253] op_sel_hi:[1,0]
	v_pk_mul_f32 v[196:197], v[196:197], v[252:253] op_sel_hi:[1,0]
	v_pk_mul_f32 v[198:199], v[198:199], v[252:253] op_sel_hi:[1,0]
	v_pk_mul_f32 v[200:201], v[200:201], v[252:253] op_sel_hi:[1,0]
	v_pk_mul_f32 v[202:203], v[202:203], v[252:253] op_sel_hi:[1,0]
	v_pk_mul_f32 v[204:205], v[204:205], v[252:253] op_sel_hi:[1,0]
	v_pk_mul_f32 v[206:207], v[206:207], v[252:253] op_sel_hi:[1,0]
	v_pk_mul_f32 v[208:209], v[208:209], v[252:253] op_sel_hi:[1,0]
	v_pk_mul_f32 v[210:211], v[210:211], v[252:253] op_sel_hi:[1,0]
	v_pk_mul_f32 v[212:213], v[212:213], v[252:253] op_sel_hi:[1,0]
	v_pk_mul_f32 v[214:215], v[214:215], v[252:253] op_sel_hi:[1,0]
	v_pk_mul_f32 v[216:217], v[216:217], v[252:253] op_sel_hi:[1,0]
	v_pk_mul_f32 v[218:219], v[218:219], v[252:253] op_sel_hi:[1,0]
	v_pk_mul_f32 v[254:255], v[188:189], v[188:189]
	v_pk_fma_f32 v[254:255], v[190:191], v[190:191], v[254:255]
	v_pk_fma_f32 v[254:255], v[192:193], v[192:193], v[254:255]
	v_pk_fma_f32 v[254:255], v[194:195], v[194:195], v[254:255]
	v_pk_fma_f32 v[254:255], v[196:197], v[196:197], v[254:255]
	v_pk_fma_f32 v[254:255], v[198:199], v[198:199], v[254:255]
	v_pk_fma_f32 v[254:255], v[200:201], v[200:201], v[254:255]
	v_pk_fma_f32 v[254:255], v[202:203], v[202:203], v[254:255]
	v_pk_fma_f32 v[254:255], v[204:205], v[204:205], v[254:255]
	v_pk_fma_f32 v[254:255], v[206:207], v[206:207], v[254:255]
	v_pk_fma_f32 v[254:255], v[208:209], v[208:209], v[254:255]
	v_pk_fma_f32 v[254:255], v[210:211], v[210:211], v[254:255]
	v_pk_fma_f32 v[254:255], v[212:213], v[212:213], v[254:255]
	v_pk_fma_f32 v[254:255], v[214:215], v[214:215], v[254:255]
	v_pk_fma_f32 v[254:255], v[216:217], v[216:217], v[254:255]
	v_pk_fma_f32 v[254:255], v[218:219], v[218:219], v[254:255]
	v_add_f32_e32 v254, v254, v255
	ds_bpermute_b32 v253, v238, v254
	s_waitcnt lgkmcnt(0)
	v_add_f32_e32 v254, v254, v253
	ds_bpermute_b32 v253, v239, v254
	s_waitcnt lgkmcnt(0)
	v_add_f32_e32 v254, v254, v253
	v_mov_b32_e32 v253, 0x358637bd
	s_mov_b32 s30, 0x800000
	v_fmamk_f32 v254, v254, 0x3c000000, v253
	v_mul_f32_e32 v253, 0x4b800000, v254
	v_cmp_gt_f32_e32 vcc, s30, v254
	s_nop 1
	v_cndmask_b32_e32 v254, v254, v253, vcc
	v_rsq_f32_e32 v254, v254
	s_nop 0
	v_mul_f32_e32 v253, 0x45800000, v254
	v_cndmask_b32_e32 v254, v254, v253, vcc
	s_waitcnt vmcnt(0)
	v_pk_mul_f32 v[188:189], v[188:189], v[254:255] op_sel_hi:[1,0]
	v_pk_mul_f32 v[190:191], v[190:191], v[254:255] op_sel_hi:[1,0]
	v_pk_mul_f32 v[188:189], v[4:5], v[188:189]
	v_pk_mul_f32 v[190:191], v[6:7], v[190:191]
	v_cvt_pk_bf16_f32 v188, v188, v189
	v_cvt_pk_bf16_f32 v189, v190, v191
	global_store_dwordx2 v236, v[188:189], s[40:41] offset:0
	v_pk_mul_f32 v[192:193], v[192:193], v[254:255] op_sel_hi:[1,0]
	v_pk_mul_f32 v[194:195], v[194:195], v[254:255] op_sel_hi:[1,0]
	v_pk_mul_f32 v[192:193], v[8:9], v[192:193]
	v_pk_mul_f32 v[194:195], v[10:11], v[194:195]
	v_cvt_pk_bf16_f32 v192, v192, v193
	v_cvt_pk_bf16_f32 v193, v194, v195
	global_store_dwordx2 v236, v[192:193], s[40:41] offset:32
	v_pk_mul_f32 v[196:197], v[196:197], v[254:255] op_sel_hi:[1,0]
	v_pk_mul_f32 v[198:199], v[198:199], v[254:255] op_sel_hi:[1,0]
	v_pk_mul_f32 v[196:197], v[12:13], v[196:197]
	v_pk_mul_f32 v[198:199], v[14:15], v[198:199]
	v_cvt_pk_bf16_f32 v196, v196, v197
	v_cvt_pk_bf16_f32 v197, v198, v199
	global_store_dwordx2 v236, v[196:197], s[40:41] offset:64
	v_pk_mul_f32 v[200:201], v[200:201], v[254:255] op_sel_hi:[1,0]
	v_pk_mul_f32 v[202:203], v[202:203], v[254:255] op_sel_hi:[1,0]
	v_pk_mul_f32 v[200:201], v[16:17], v[200:201]
	v_pk_mul_f32 v[202:203], v[18:19], v[202:203]
	v_cvt_pk_bf16_f32 v200, v200, v201
	v_cvt_pk_bf16_f32 v201, v202, v203
	global_store_dwordx2 v236, v[200:201], s[40:41] offset:96
	v_pk_mul_f32 v[204:205], v[204:205], v[254:255] op_sel_hi:[1,0]
	v_pk_mul_f32 v[206:207], v[206:207], v[254:255] op_sel_hi:[1,0]
	v_pk_mul_f32 v[204:205], v[20:21], v[204:205]
	v_pk_mul_f32 v[206:207], v[22:23], v[206:207]
	v_cvt_pk_bf16_f32 v204, v204, v205
	v_cvt_pk_bf16_f32 v205, v206, v207
	global_store_dwordx2 v236, v[204:205], s[40:41] offset:128
	v_pk_mul_f32 v[208:209], v[208:209], v[254:255] op_sel_hi:[1,0]
	v_pk_mul_f32 v[210:211], v[210:211], v[254:255] op_sel_hi:[1,0]
	v_pk_mul_f32 v[208:209], v[24:25], v[208:209]
	v_pk_mul_f32 v[210:211], v[26:27], v[210:211]
	v_cvt_pk_bf16_f32 v208, v208, v209
	v_cvt_pk_bf16_f32 v209, v210, v211
	global_store_dwordx2 v236, v[208:209], s[40:41] offset:160
	v_pk_mul_f32 v[212:213], v[212:213], v[254:255] op_sel_hi:[1,0]
	v_pk_mul_f32 v[214:215], v[214:215], v[254:255] op_sel_hi:[1,0]
	v_pk_mul_f32 v[212:213], v[28:29], v[212:213]
	v_pk_mul_f32 v[214:215], v[30:31], v[214:215]
	v_cvt_pk_bf16_f32 v212, v212, v213
	v_cvt_pk_bf16_f32 v213, v214, v215
	global_store_dwordx2 v236, v[212:213], s[40:41] offset:192
	v_pk_mul_f32 v[216:217], v[216:217], v[254:255] op_sel_hi:[1,0]
	v_pk_mul_f32 v[218:219], v[218:219], v[254:255] op_sel_hi:[1,0]
	v_pk_mul_f32 v[216:217], v[32:33], v[216:217]
	v_pk_mul_f32 v[218:219], v[34:35], v[218:219]
	v_cvt_pk_bf16_f32 v216, v216, v217
	v_cvt_pk_bf16_f32 v217, v218, v219
	global_store_dwordx2 v236, v[216:217], s[40:41] offset:224
	s_barrier
	s_add_i32 s20, s20, s46
	s_cmpk_lt_i32 s20, 0x200
	s_cbranch_scc1 .Latt_unit
